# scan: masked P block computed by the priority-raised half (waves 4-7), other half issues the prefetch loads
# baseline (speedup 1.0000x reference)
; DEV int tidx() { return tidx_full() & 255; }
; DEV void scan_item_mfma(const Params& p, int g, int item, char* smem) {
;   const int L = g ? 8192 : 4096;
;   const int NC = L / 64;
;   const int vs = item & 3, dir = (item >> 2) & 1, h = (item >> 3) & 3, b = item >> 5;
;   char* Qs = smem;
;   char* Ks = Qs + 17408;
;   char* KTs = Ks + 17408;
;   char* Vts = KTs + 18432;
;   char* Ps = Vts + 4608;
;   char* Sts = Ps + 9216;
;   float* decs = (float*)(Sts + 8704);
;   u16* PHG = (u16*)(p.ws + OFF_PHG);
;   const u16* QK = (const u16*)(p.out + (size_t)g * NTOK * D);
;   const u16* Qp = QK + (size_t)(2 * dir) * NTOK * 512;
;   const u16* Kp = Qp + (size_t)NTOK * 512;
;   const u16* KT = (const u16*)(p.ws + OFF_KT);
;   const float* DEC = (const float*)(p.ws + OFF_DEC);
;   const int tid = tidx();
;   const int wave = __builtin_amdgcn_readfirstlane(tid >> 6);
;   const int lane = tid & 63, r = lane & 31, hh = lane >> 5;
;   __syncthreads();
;   for (int e = tid; e < 8704 / 16; e += 256) ((uint4*)Sts)[e] = make_uint4(0, 0, 0, 0);
;   f32x16 accS[2];
; #pragma unroll
;   for (int t = 0; t < 2; ++t)
; #pragma unroll
;     for (int i = 0; i < 16; ++i) accS[t][i] = 0.f;
;   const int ocol = (dir ? 1024 : 0) + h * 128 + vs * 32;
;   uint4 q0, q1, q2, q3, k0, k1, k2, k3, t0, t1, t2, t3, vv;
;   float dd = 0.f;
;   const int qrow = tid >> 4, qc = tid & 15;
;   const int trow = tid >> 3, tc = tid & 7;
;   const int vrow = tid >> 2, vc = tid & 3;
.LBB0_667:
	s_movk_i32 s40, 0x1400
	s_or_b64 exec, exec, s[0:1]
	s_and_b64 s[0:1], s[66:67], exec
	v_readfirstlane_b32 s24, v202
	s_cselect_b32 s0, 0x100, s61
	s_lshr_b32 s26, s24, 8
	s_cmp_ge_i32 s81, s0
	s_waitcnt lgkmcnt(0)
	s_barrier
	s_cbranch_scc1 .LBB0_720
	v_writelane_b32 v160, s0, 0
	v_writelane_b32 v160, s1, 1
	v_writelane_b32 v160, s2, 2
	v_writelane_b32 v160, s3, 3
	v_writelane_b32 v160, s4, 4
	v_writelane_b32 v160, s5, 5
	v_writelane_b32 v160, s6, 6
	v_writelane_b32 v160, s7, 7
	v_writelane_b32 v160, s8, 8
	v_writelane_b32 v160, s9, 9
	v_writelane_b32 v160, s10, 10
	v_writelane_b32 v160, s11, 11
	v_writelane_b32 v160, s12, 12
	v_writelane_b32 v160, s13, 13
	v_writelane_b32 v160, s14, 14
	v_writelane_b32 v160, s15, 15
	v_writelane_b32 v160, s16, 16
	v_writelane_b32 v160, s17, 17
	v_writelane_b32 v160, s18, 18
	v_writelane_b32 v160, s19, 19
	v_writelane_b32 v160, s20, 20
	v_writelane_b32 v160, s21, 21
	v_writelane_b32 v160, s22, 22
	v_writelane_b32 v160, s23, 23
	v_writelane_b32 v160, s24, 24
	v_writelane_b32 v160, s25, 25
	v_writelane_b32 v160, s26, 26
	v_writelane_b32 v160, s27, 27
	v_writelane_b32 v160, s28, 28
	v_writelane_b32 v160, s29, 29
	v_writelane_b32 v160, s30, 30
	v_writelane_b32 v160, s31, 31
	v_writelane_b32 v160, s33, 33
	v_writelane_b32 v160, s34, 34
	v_writelane_b32 v160, s35, 35
	v_writelane_b32 v160, s36, 36
	v_writelane_b32 v160, s37, 37
	v_writelane_b32 v160, s38, 38
	v_writelane_b32 v160, s39, 39
	v_writelane_b32 v160, s40, 40
	v_writelane_b32 v160, s41, 41
	v_writelane_b32 v160, s42, 42
	v_writelane_b32 v160, s43, 43
	v_writelane_b32 v160, s44, 44
	v_writelane_b32 v160, s45, 45
	v_writelane_b32 v160, s46, 46
	v_writelane_b32 v160, s47, 47
	v_writelane_b32 v160, s48, 48
	v_writelane_b32 v160, s49, 49
	v_writelane_b32 v160, s50, 50
	v_writelane_b32 v160, s51, 51
	v_writelane_b32 v160, s52, 52
	v_writelane_b32 v160, s53, 53
	v_writelane_b32 v160, s54, 54
	v_writelane_b32 v160, s55, 55
	v_writelane_b32 v160, s56, 56
	v_writelane_b32 v160, s57, 57
	v_writelane_b32 v160, s58, 58
	v_writelane_b32 v160, s59, 59
	v_writelane_b32 v160, s60, 60
	v_writelane_b32 v160, s61, 61
	v_writelane_b32 v160, s62, 62
	v_writelane_b32 v160, s63, 63
	v_writelane_b32 v161, s64, 0
	v_writelane_b32 v161, s65, 1
	v_writelane_b32 v161, s66, 2
	v_writelane_b32 v161, s67, 3
	v_writelane_b32 v161, s68, 4
	v_writelane_b32 v161, s69, 5
	v_writelane_b32 v161, s70, 6
	v_writelane_b32 v161, s71, 7
	v_writelane_b32 v161, s72, 8
	v_writelane_b32 v161, s73, 9
	s_barrier
	s_add_i32 s2, s26, s81
	s_and_b32 s3, s2, 3
	s_bfe_u32 s4, s2, 0x10002
	s_bfe_u32 s5, s2, 0x20003
	s_lshr_b32 s6, s2, 5
	s_and_b64 s[0:1], s[66:67], exec
	s_cselect_b32 s7, 64, 0x80
	s_bfe_u32 s9, s24, 0x20006
	s_mul_i32 s31, s26, 0x3600
	s_add_u32 s31, s31, 0xf400
	v_and_b32_e32 v53, 0xff, v202
	v_and_b32_e32 v54, 63, v202
	v_and_b32_e32 v55, 31, v202
	v_bfe_u32 v109, v202, 5, 1
	v_bfe_u32 v110, v202, 6, 2
	v_and_b32_e32 v111, 0x1ff, v202
	v_lshrrev_b32_e32 v220, 4, v111
	v_and_b32_e32 v221, 15, v111
	v_lshlrev_b32_e32 v219, 4, v221
	v_lshl_add_u32 v209, v220, 10, v219
	v_add_u32_e32 v210, 0x8000, v209
	v_mul_u32_u24_e32 v248, 0x110, v220
	v_add_u32_e32 v234, v248, v219
	v_lshrrev_b32_e32 v220, 3, v111
	v_and_b32_e32 v221, 7, v111
	v_lshlrev_b32_e32 v219, 4, v221
	v_lshl_add_u32 v213, v220, 7, v219
	v_add_u32_e32 v214, 0x2000, v213
	v_mul_u32_u24_e32 v248, 0x90, v220
	v_add_u32_e32 v235, v248, v219
	v_lshrrev_b32_e32 v220, 2, v53
	v_and_b32_e32 v221, 3, v53
	v_mul_u32_u24_e32 v219, 0x1400, v220
	v_lshl_add_u32 v215, v221, 4, v219
	v_mul_u32_u24_e32 v219, 0x480, v221
	v_lshl_add_u32 v219, v220, 1, v219
	v_add_u32_e32 v236, s31, v219
	v_and_b32_e32 v220, 0x7f, v53
	v_lshlrev_b32_e32 v216, 2, v220
	v_add_u32_e32 v237, s31, v216
	v_mul_u32_u24_e32 v220, 0x110, v55
	v_mul_u32_u24_e32 v221, 0x90, v55
	v_lshlrev_b32_e32 v219, 4, v109
	v_add_u32_e32 v164, v220, v219
	v_add3_u32 v245, v220, v219, s31
	v_add3_u32 v244, v221, v219, s31
	v_add_u32_e32 v111, v221, v219
	v_lshrrev_b32_e32 v248, 1, v110
	v_mul_u32_u24_e32 v248, 0x2200, v248
	v_add_u32_e32 v240, v164, v248
	v_and_b32_e32 v248, 1, v110
	v_mul_u32_u24_e32 v248, 0x2200, v248
	v_add_u32_e32 v242, v164, v248
	v_mul_u32_u24_e32 v248, 0x2200, v110
	v_add_u32_e32 v241, v164, v248
	v_mul_u32_u24_e32 v248, 0x1200, v110
	v_add_u32_e32 v243, v111, v248
	v_lshrrev_b32_e32 v248, 1, v110
	v_mul_u32_u24_e32 v248, 0x1200, v248
	v_add_u32_e32 v239, v221, v248
	v_and_b32_e32 v248, 1, v110
	v_lshlrev_b32_e32 v248, 6, v248
	v_lshl_add_u32 v248, v109, 3, v248
	v_add_u32_e32 v239, v239, v248
	v_subrev_u32_e32 v248, 2, v110
	v_lshlrev_b32_e32 v219, 7, v248
	v_lshl_add_u32 v219, v109, 3, v219
	v_add3_u32 v238, v220, v219, s31
	v_mul_u32_u24_e32 v219, 0x2400, v248
	v_add_u32_e32 v207, v111, v219
	v_lshlrev_b32_e32 v219, 8, v248
	v_lshl_add_u32 v219, v109, 4, v219
	v_add_u32_e32 v208, s31, v219
	v_lshl_add_u32 v219, v110, 5, v55
	v_mul_u32_u24_e32 v219, 0x1400, v219
	v_lshl_add_u32 v217, v109, 3, v219
	v_lshlrev_b32_e32 v219, 2, v109
	v_sub_u32_e32 v218, v55, v219
	s_cmp_eq_u32 s4, 0
	s_cbranch_scc0 .Lscan_d1
; DEV void scan_item_mfma(const Params& p, int g, int item, char* smem) {
;     ...
;   __syncthreads();
;   for (int e = tid; e < 8704 / 16; e += 256) ((uint4*)Sts)[e] = make_uint4(0, 0, 0, 0);
;   f32x16 accS[2];
; #pragma unroll
;   for (int t = 0; t < 2; ++t)
; #pragma unroll
;     for (int i = 0; i < 16; ++i) accS[t][i] = 0.f;
;   const int ocol = (dir ? 1024 : 0) + h * 128 + vs * 32;
;   uint4 q0, q1, q2, q3, k0, k1, k2, k3, t0, t1, t2, t3, vv;
;   float dd = 0.f;
;   const int qrow = tid >> 4, qc = tid & 15;
;   const int trow = tid >> 3, tc = tid & 7;
;   const int vrow = tid >> 2, vc = tid & 3;
;     ...
;   unsigned opk[8] = {0u, 0u, 0u, 0u, 0u, 0u, 0u, 0u};
;   size_t otok = 0;
;   SCAN_ISSUE(dir ? NC - 1 : 0);
	s_mul_i32 s11, s6, s7
	s_mov_b32 s12, s64
	s_mov_b32 s13, s65
	s_mul_i32 s0, s11, 0x10000
	s_add_u32 s12, s12, s0
	s_addc_u32 s13, s13, 0
	s_mul_i32 s0, s5, 0x100
	s_add_u32 s12, s12, s0
	s_addc_u32 s13, s13, 0
	s_add_u32 s14, s12, 0x2000000
	s_addc_u32 s15, s13, 0
	s_add_u32 s16, s88, 0x3d4c100
	s_addc_u32 s17, s89, 0
	s_mul_i32 s0, s11, 0x20000
	s_add_u32 s16, s16, s0
	s_addc_u32 s17, s17, 0
	s_mul_i32 s0, s5, 0x4000
	s_add_u32 s16, s16, s0
	s_addc_u32 s17, s17, 0
	s_add_u32 s18, s88, 0xdd4c500
	s_addc_u32 s19, s89, 0
	s_mul_i32 s0, s11, 0x50000
	s_add_u32 s18, s18, s0
	s_addc_u32 s19, s19, 0
	s_mul_i32 s0, s5, 0x100
	s_add_u32 s18, s18, s0
	s_addc_u32 s19, s19, 0
	s_mul_i32 s0, s3, 0x40
	s_add_u32 s18, s18, s0
	s_addc_u32 s19, s19, 0
	s_add_u32 s20, s88, 0x3b4c100
	s_addc_u32 s21, s89, 0
	s_mul_i32 s0, s11, 0x800
	s_add_u32 s20, s20, s0
	s_addc_u32 s21, s21, 0
	s_mul_i32 s0, s5, 0x200
	s_add_u32 s20, s20, s0
	s_addc_u32 s21, s21, 0
	s_add_u32 s22, s88, 0xdd4c100
	s_addc_u32 s23, s89, 0
	s_mul_i32 s0, s11, 0x50000
	s_add_u32 s22, s22, s0
	s_addc_u32 s23, s23, 0
	s_mul_i32 s0, s5, 0x100
	s_add_u32 s22, s22, s0
	s_addc_u32 s23, s23, 0
	s_mul_i32 s0, s3, 0x40
	s_add_u32 s22, s22, s0
	s_addc_u32 s23, s23, 0
	v_cmp_le_i32_e64 s[34:35], 0, v218
	v_cmp_le_i32_e64 s[36:37], 1, v218
	v_cmp_le_i32_e64 s[38:39], 2, v218
	v_cmp_le_i32_e64 s[40:41], 3, v218
	v_cmp_le_i32_e64 s[42:43], 8, v218
	v_cmp_le_i32_e64 s[44:45], 9, v218
	v_cmp_le_i32_e64 s[46:47], 10, v218
	v_cmp_le_i32_e64 s[48:49], 11, v218
	v_cmp_le_i32_e64 s[50:51], 16, v218
	v_cmp_le_i32_e64 s[52:53], 17, v218
	v_cmp_le_i32_e64 s[54:55], 18, v218
	v_cmp_le_i32_e64 s[56:57], 19, v218
	v_cmp_le_i32_e64 s[58:59], 24, v218
	v_cmp_le_i32_e64 s[60:61], 25, v218
	v_cmp_le_i32_e64 s[62:63], 26, v218
	v_cmp_le_i32_e64 s[64:65], 27, v218
	v_mov_b32_e32 v144, 0
	v_mov_b32_e32 v145, 0
	v_mov_b32_e32 v146, 0
	v_mov_b32_e32 v147, 0
	v_mov_b64_e32 v[112:113], v[144:145]
	v_mov_b64_e32 v[114:115], v[144:145]
	v_mov_b64_e32 v[116:117], v[144:145]
	v_mov_b64_e32 v[118:119], v[144:145]
	v_mov_b64_e32 v[120:121], v[144:145]
	v_mov_b64_e32 v[122:123], v[144:145]
	v_mov_b64_e32 v[124:125], v[144:145]
	v_mov_b64_e32 v[126:127], v[144:145]
	v_mov_b64_e32 v[128:129], v[144:145]
	v_mov_b64_e32 v[130:131], v[144:145]
	v_mov_b64_e32 v[132:133], v[144:145]
	v_mov_b64_e32 v[134:135], v[144:145]
	v_mov_b64_e32 v[136:137], v[144:145]
	v_mov_b64_e32 v[138:139], v[144:145]
	v_mov_b64_e32 v[140:141], v[144:145]
	v_mov_b64_e32 v[142:143], v[144:145]
	v_lshl_add_u32 v220, v53, 5, s31
	ds_write_b128 v220, v[144:147] offset:4608
	ds_write_b128 v220, v[144:147] offset:4624
	v_and_b32_e32 v221, 31, v53
	v_lshl_add_u32 v221, v221, 4, s31
	ds_write_b128 v221, v[144:147] offset:12800
	s_cmp_eq_u32 s26, 1
	s_cbranch_scc0 .Lsc0_nz
	s_cmp_eq_u32 s9, 1
	s_cbranch_scc0 .Lsc0_nz
	v_mul_u32_u24_e32 v219, 24, v109
	v_add_u32_e32 v219, v239, v219
	ds_write_b128 v219, v[144:147] offset:53248
	ds_write_b128 v219, v[144:147] offset:53264
.Lsc0_nz:
	s_mov_b32 s25, s9
	s_cmp_eq_u32 s9, 1
	s_cselect_b32 s25, 4, s25
	s_cmp_eq_u32 s26, 1
	s_cselect_b32 s25, s25, 4
	global_load_dwordx4 v[0:3], v209, s[12:13]
	global_load_dwordx4 v[4:7], v210, s[12:13]
	global_load_dwordx4 v[8:11], v209, s[14:15]
	global_load_dwordx4 v[12:15], v210, s[14:15]
	global_load_dwordx4 v[16:19], v213, s[16:17]
	global_load_dwordx4 v[20:23], v214, s[16:17]
	global_load_dwordx4 v[24:27], v215, s[18:19]
	global_load_dword v28, v216, s[20:21]
	s_sub_i32 s10, s7, 1
	s_cmp_gt_i32 s10, 0
	s_cselect_b32 s1, 1, 0
	s_sub_i32 s10, s10, s1
	s_mul_i32 s0, s1, 0x10000
	s_add_u32 s12, s12, s0
	s_addc_u32 s13, s13, 0
	s_mul_i32 s0, s1, 0x10000
	s_add_u32 s14, s14, s0
	s_addc_u32 s15, s15, 0
	s_mul_i32 s0, s1, 0x20000
	s_add_u32 s16, s16, s0
	s_addc_u32 s17, s17, 0
	s_mul_i32 s0, s1, 0x50000
	s_add_u32 s18, s18, s0
	s_addc_u32 s19, s19, 0
	s_mul_i32 s0, s1, 0x800
	s_add_u32 s20, s20, s0
	s_addc_u32 s21, s21, 0
	global_load_dwordx4 v[32:35], v209, s[12:13]
	global_load_dwordx4 v[36:39], v210, s[12:13]
	global_load_dwordx4 v[40:43], v209, s[14:15]
	global_load_dwordx4 v[44:47], v210, s[14:15]
	global_load_dwordx4 v[48:51], v213, s[16:17]
	global_load_dwordx4 v[52:55], v214, s[16:17]
	global_load_dwordx4 v[56:59], v215, s[18:19]
	global_load_dword v60, v216, s[20:21]
	s_cmp_lt_u32 s9, 2
	s_cbranch_scc0 .Lsc0_w1sfa
	s_waitcnt vmcnt(8)
	s_branch .Lsc0_w1efa

; DEV void scan_item_mfma(const Params& p, int g, int item, char* smem) {
;     ...
;   const int ocol = (dir ? 1024 : 0) + h * 128 + vs * 32;
;   uint4 q0, q1, q2, q3, k0, k1, k2, k3, t0, t1, t2, t3, vv;
;   float dd = 0.f;
;   const int qrow = tid >> 4, qc = tid & 15;
;   const int trow = tid >> 3, tc = tid & 7;
;   const int vrow = tid >> 2, vc = tid & 3;
;     ...
;   unsigned opk[8] = {0u, 0u, 0u, 0u, 0u, 0u, 0u, 0u};
;   size_t otok = 0;
;   SCAN_ISSUE(dir ? NC - 1 : 0);
;   for (int ci = 0; ci < NC; ++ci) {
;     const int n = dir ? NC - 1 - ci : ci;
;     const size_t tok0 = ((size_t)b * NC + n) * 64;
.Lscan_d1:
	s_mul_i32 s11, s6, s7
	s_add_i32 s11, s11, s7
	s_sub_i32 s11, s11, 1
	s_add_u32 s12, s64, 0x4000000
	s_addc_u32 s13, s65, 0
	s_mul_i32 s0, s11, 0x10000
	s_add_u32 s12, s12, s0
	s_addc_u32 s13, s13, 0
	s_mul_i32 s0, s5, 0x100
	s_add_u32 s12, s12, s0
	s_addc_u32 s13, s13, 0
	s_add_u32 s14, s12, 0x2000000
	s_addc_u32 s15, s13, 0
	s_add_u32 s16, s88, 0x3d5c100
	s_addc_u32 s17, s89, 0
	s_mul_i32 s0, s11, 0x20000
	s_add_u32 s16, s16, s0
	s_addc_u32 s17, s17, 0
	s_mul_i32 s0, s5, 0x4000
	s_add_u32 s16, s16, s0
	s_addc_u32 s17, s17, 0
	s_add_u32 s18, s88, 0xdd4c500
	s_addc_u32 s19, s89, 0
	s_mul_i32 s0, s11, 0x50000
	s_add_u32 s18, s18, s0
	s_addc_u32 s19, s19, 0
	s_mul_i32 s0, s5, 0x100
	s_add_u32 s18, s18, s0
	s_addc_u32 s19, s19, 0
	s_mul_i32 s0, s3, 0x40
	s_add_u32 s18, s18, s0
	s_addc_u32 s19, s19, 0
	s_add_u32 s20, s88, 0x3c4c100
	s_addc_u32 s21, s89, 0
	s_mul_i32 s0, s11, 0x800
	s_add_u32 s20, s20, s0
	s_addc_u32 s21, s21, 0
	s_mul_i32 s0, s5, 0x200
	s_add_u32 s20, s20, s0
	s_addc_u32 s21, s21, 0
	s_add_u32 s22, s88, 0xdd4c900
	s_addc_u32 s23, s89, 0
	s_mul_i32 s0, s11, 0x50000
	s_add_u32 s22, s22, s0
	s_addc_u32 s23, s23, 0
	s_mul_i32 s0, s5, 0x100
	s_add_u32 s22, s22, s0
	s_addc_u32 s23, s23, 0
	s_mul_i32 s0, s3, 0x40
	s_add_u32 s22, s22, s0
	s_addc_u32 s23, s23, 0
	v_cmp_ge_i32_e64 s[34:35], 0, v218
	v_cmp_ge_i32_e64 s[36:37], 1, v218
	v_cmp_ge_i32_e64 s[38:39], 2, v218
	v_cmp_ge_i32_e64 s[40:41], 3, v218
	v_cmp_ge_i32_e64 s[42:43], 8, v218
	v_cmp_ge_i32_e64 s[44:45], 9, v218
	v_cmp_ge_i32_e64 s[46:47], 10, v218
	v_cmp_ge_i32_e64 s[48:49], 11, v218
	v_cmp_ge_i32_e64 s[50:51], 16, v218
	v_cmp_ge_i32_e64 s[52:53], 17, v218
	v_cmp_ge_i32_e64 s[54:55], 18, v218
	v_cmp_ge_i32_e64 s[56:57], 19, v218
	v_cmp_ge_i32_e64 s[58:59], 24, v218
	v_cmp_ge_i32_e64 s[60:61], 25, v218
	v_cmp_ge_i32_e64 s[62:63], 26, v218
	v_cmp_ge_i32_e64 s[64:65], 27, v218
	v_mov_b32_e32 v144, 0
	v_mov_b32_e32 v145, 0
	v_mov_b32_e32 v146, 0
	v_mov_b32_e32 v147, 0
	v_mov_b64_e32 v[112:113], v[144:145]
	v_mov_b64_e32 v[114:115], v[144:145]
	v_mov_b64_e32 v[116:117], v[144:145]
	v_mov_b64_e32 v[118:119], v[144:145]
	v_mov_b64_e32 v[120:121], v[144:145]
	v_mov_b64_e32 v[122:123], v[144:145]
	v_mov_b64_e32 v[124:125], v[144:145]
	v_mov_b64_e32 v[126:127], v[144:145]
	v_mov_b64_e32 v[128:129], v[144:145]
	v_mov_b64_e32 v[130:131], v[144:145]
	v_mov_b64_e32 v[132:133], v[144:145]
	v_mov_b64_e32 v[134:135], v[144:145]
	v_mov_b64_e32 v[136:137], v[144:145]
	v_mov_b64_e32 v[138:139], v[144:145]
	v_mov_b64_e32 v[140:141], v[144:145]
	v_mov_b64_e32 v[142:143], v[144:145]
	v_lshl_add_u32 v220, v53, 5, s31
	ds_write_b128 v220, v[144:147] offset:4608
	ds_write_b128 v220, v[144:147] offset:4624
	v_and_b32_e32 v221, 31, v53
	v_lshl_add_u32 v221, v221, 4, s31
	ds_write_b128 v221, v[144:147] offset:12800
	s_cmp_eq_u32 s26, 1
	s_cbranch_scc0 .Lsc1_nz
	s_cmp_eq_u32 s9, 2
	s_cbranch_scc0 .Lsc1_nz
	v_mul_u32_u24_e32 v219, 24, v109
	v_add_u32_e32 v219, v239, v219
	ds_write_b128 v219, v[144:147] offset:53248
	ds_write_b128 v219, v[144:147] offset:53264
.Lsc1_nz:
	s_mov_b32 s25, s9
	s_cmp_eq_u32 s9, 2
	s_cselect_b32 s25, 4, s25
	s_cmp_eq_u32 s26, 1
	s_cselect_b32 s25, s25, 4
	global_load_dwordx4 v[0:3], v209, s[12:13]
	global_load_dwordx4 v[4:7], v210, s[12:13]
	global_load_dwordx4 v[8:11], v209, s[14:15]
	global_load_dwordx4 v[12:15], v210, s[14:15]
	global_load_dwordx4 v[16:19], v213, s[16:17]
	global_load_dwordx4 v[20:23], v214, s[16:17]
	global_load_dwordx4 v[24:27], v215, s[18:19]
	global_load_dword v28, v216, s[20:21]
	s_sub_i32 s10, s7, 1
	s_cmp_gt_i32 s10, 0
	s_cselect_b32 s1, 1, 0
	s_sub_i32 s10, s10, s1
	s_mul_i32 s0, s1, 0x10000
	s_sub_u32 s12, s12, s0
	s_subb_u32 s13, s13, 0
	s_mul_i32 s0, s1, 0x10000
	s_sub_u32 s14, s14, s0
	s_subb_u32 s15, s15, 0
	s_mul_i32 s0, s1, 0x20000
	s_sub_u32 s16, s16, s0
	s_subb_u32 s17, s17, 0
	s_mul_i32 s0, s1, 0x50000
	s_sub_u32 s18, s18, s0
	s_subb_u32 s19, s19, 0
	s_mul_i32 s0, s1, 0x800
	s_sub_u32 s20, s20, s0
	s_subb_u32 s21, s21, 0
	global_load_dwordx4 v[32:35], v209, s[12:13]
	global_load_dwordx4 v[36:39], v210, s[12:13]
	global_load_dwordx4 v[40:43], v209, s[14:15]
	global_load_dwordx4 v[44:47], v210, s[14:15]
	global_load_dwordx4 v[48:51], v213, s[16:17]
	global_load_dwordx4 v[52:55], v214, s[16:17]
	global_load_dwordx4 v[56:59], v215, s[18:19]
	global_load_dword v60, v216, s[20:21]
	s_cmp_lt_u32 s9, 2
	s_cbranch_scc0 .Lsc1_w1sfa
	s_waitcnt vmcnt(8)
	s_branch .Lsc1_w1efa
